# removed the per-MFMA-cluster s_setprio toggling from the GEMM main loops
# speedup vs baseline: 1.0088x; 1.0078x over previous
; #define PG8_STAGE(bufoff, gbase, voff) do { _Pragma("unroll") for (int _i = 0; _i < 2; ++_i) \
;         __builtin_amdgcn_global_load_lds((const unsigned*)((const char*)(gbase) + (voff)[_i]), (LAS unsigned*)(lds + (bufoff) + ldsw + _i * 8192), 16, 0, 0); } while (0)
; #define PG8_LDA(dst, b, h) do { _Pragma("unroll") for (int m = 0; m < 4; ++m) _Pragma("unroll") for (int k = 0; k < 2; ++k) dst[m][k] = *(const LAS bf16x8*)(lds + PG8_SA(b, h) + aoff + m * 2048 + k * 1024); } while (0)
; #define PG8_LDB(dst, b, h) do { _Pragma("unroll") for (int n = 0; n < 2; ++n) _Pragma("unroll") for (int k = 0; k < 2; ++k) dst[n][k] = *(const LAS bf16x8*)(lds + PG8_SB(b, h) + boff + n * 2048 + k * 1024); } while (0)
; #define PG8_MMA(ai, bj, At, Bt) do { __builtin_amdgcn_s_setprio(1); _Pragma("unroll") for (int m = 0; m < 4; ++m) _Pragma("unroll") for (int n = 0; n < 2; ++n) _Pragma("unroll") for (int k = 0; k < 2; ++k) \
;         acc[ai][bj][m][n] = __builtin_amdgcn_mfma_f32_16x16x32_bf16(Bt[n][k], At[m][k], acc[ai][bj][m][n], 0, 0, 0); __builtin_amdgcn_s_setprio(0); } while (0)
; #define PG8_WAIT_V(n) asm volatile("s_waitcnt vmcnt(" #n ")" ::: "memory")
; #define PG8_WAIT_L(n) asm volatile("s_waitcnt lgkmcnt(" #n ")" ::: "memory")
; #define PG8_BAR __builtin_amdgcn_s_barrier()
; #define PG8_SCHED __builtin_amdgcn_sched_barrier(0)
; template <class Epi, class Sched>
; __device__ __forceinline__ void gemm_phase(LAS unsigned char* lds, const Gemm g, const Sched& S, const Epi& E) {
;     ...
;             PG8_LDB(B0, 0, 0); PG8_LDB(B1, 0, 1); PG8_SCHED; PG8_LDA(At, 0, 0); PG8_STAGE(PG8_SA(1, 1), a1 + hstepA, voffA);
;             PG8_WAIT_V(8); PG8_WAIT_L(0); PG8_BAR; PG8_MMA(0, 0, At, B0); PG8_MMA(0, 1, At, B1); PG8_BAR; PG8_SCHED;
;             PG8_LDA(At, 0, 1); PG8_STAGE(PG8_SB(0, 0), b2, voffB); PG8_STAGE(PG8_SB(0, 1), b2 + hstepB, voffB); PG8_STAGE(PG8_SA(0, 0), a2, voffA);
.LBB0_261:
	s_add_u32 s14, s42, 0xfffc0080
	s_addc_u32 s15, s43, -1
	s_add_i32 s63, 0, 0x10000
	s_cmp_eq_u32 s62, 12
	s_cselect_b32 s17, s18, s15
	s_cselect_b32 s16, s19, s14
	v_add_u32_e32 v144, s63, v162
	s_cselect_b32 s15, s53, s61
	s_cselect_b32 s14, s55, s60
	s_add_i32 s71, 0, 0x14000
	ds_read_b128 v[140:143], v144
	ds_read_b128 v[156:159], v144 offset:1024
	ds_read_b128 v[166:169], v144 offset:2048
	ds_read_b128 v[170:173], v144 offset:3072
	v_add_u32_e32 v144, s71, v162
	ds_read_b128 v[174:177], v144
	ds_read_b128 v[180:183], v144 offset:1024
	ds_read_b128 v[192:195], v144 offset:2048
	ds_read_b128 v[196:199], v144 offset:3072
	v_lshl_add_u64 v[232:233], s[42:43], 0, v[136:137]
	s_add_i32 m0, s8, 0xc000
	ds_read_b128 v[200:203], v164
	ds_read_b128 v[204:207], v164 offset:1024
	ds_read_b128 v[208:211], v164 offset:2048
	ds_read_b128 v[212:215], v164 offset:3072
	ds_read_b128 v[216:219], v164 offset:4096
	ds_read_b128 v[220:223], v164 offset:5120
	ds_read_b128 v[224:227], v164 offset:6144
	ds_read_b128 v[228:231], v164 offset:7168
	global_load_lds_dwordx4 v[232:233], off
	v_lshl_add_u64 v[232:233], s[42:43], 0, v[138:139]
	s_add_i32 m0, s8, 0xe000
	s_nop 0
	global_load_lds_dwordx4 v[232:233], off
	s_waitcnt vmcnt(8)
	s_waitcnt lgkmcnt(0)
	s_barrier
	s_waitcnt lgkmcnt(0)
	v_mfma_f32_16x16x32_bf16 v[124:127], v[140:143], v[200:203], v[124:127]
	v_mfma_f32_16x16x32_bf16 v[120:123], v[166:169], v[200:203], v[120:123]
	v_mfma_f32_16x16x32_bf16 v[108:111], v[140:143], v[208:211], v[108:111]
	v_mfma_f32_16x16x32_bf16 v[104:107], v[166:169], v[208:211], v[104:107]
	v_mfma_f32_16x16x32_bf16 v[92:95], v[140:143], v[216:219], v[92:95]
	v_mfma_f32_16x16x32_bf16 v[88:91], v[166:169], v[216:219], v[88:91]
	v_mfma_f32_16x16x32_bf16 v[76:79], v[140:143], v[224:227], v[76:79]
	v_mfma_f32_16x16x32_bf16 v[72:75], v[166:169], v[224:227], v[72:75]
	v_mfma_f32_16x16x32_bf16 v[124:127], v[156:159], v[204:207], v[124:127]
	v_mfma_f32_16x16x32_bf16 v[120:123], v[170:173], v[204:207], v[120:123]
	v_mfma_f32_16x16x32_bf16 v[108:111], v[156:159], v[212:215], v[108:111]
	v_mfma_f32_16x16x32_bf16 v[104:107], v[170:173], v[212:215], v[104:107]
	v_mfma_f32_16x16x32_bf16 v[92:95], v[156:159], v[220:223], v[92:95]
	v_mfma_f32_16x16x32_bf16 v[88:91], v[170:173], v[220:223], v[88:91]
	v_mfma_f32_16x16x32_bf16 v[76:79], v[156:159], v[228:231], v[76:79]
	v_mfma_f32_16x16x32_bf16 v[72:75], v[170:173], v[228:231], v[72:75]
	v_mfma_f32_16x16x32_bf16 v[116:119], v[174:177], v[200:203], v[116:119]
	v_mfma_f32_16x16x32_bf16 v[112:115], v[192:195], v[200:203], v[112:115]
	v_mfma_f32_16x16x32_bf16 v[100:103], v[174:177], v[208:211], v[100:103]
	v_mfma_f32_16x16x32_bf16 v[96:99], v[192:195], v[208:211], v[96:99]
	v_mfma_f32_16x16x32_bf16 v[84:87], v[174:177], v[216:219], v[84:87]
	v_mfma_f32_16x16x32_bf16 v[80:83], v[192:195], v[216:219], v[80:83]
	v_mfma_f32_16x16x32_bf16 v[68:71], v[174:177], v[224:227], v[68:71]
	v_mfma_f32_16x16x32_bf16 v[64:67], v[192:195], v[224:227], v[64:67]
	v_mfma_f32_16x16x32_bf16 v[116:119], v[180:183], v[204:207], v[116:119]
	v_mfma_f32_16x16x32_bf16 v[112:115], v[196:199], v[204:207], v[112:115]
	v_mfma_f32_16x16x32_bf16 v[100:103], v[180:183], v[212:215], v[100:103]
	v_mfma_f32_16x16x32_bf16 v[96:99], v[196:199], v[212:215], v[96:99]
	v_mfma_f32_16x16x32_bf16 v[84:87], v[180:183], v[220:223], v[84:87]
	v_mfma_f32_16x16x32_bf16 v[80:83], v[196:199], v[220:223], v[80:83]
	v_mfma_f32_16x16x32_bf16 v[68:71], v[180:183], v[228:231], v[68:71]
	v_mfma_f32_16x16x32_bf16 v[64:67], v[196:199], v[228:231], v[64:67]
	s_barrier
	s_add_i32 s63, s63, s6
	v_lshl_add_u64 v[232:233], s[14:15], 0, v[132:133]
	s_mov_b32 m0, s63
	ds_read_b128 v[200:203], v164 offset:16384
	ds_read_b128 v[204:207], v164 offset:17408
	ds_read_b128 v[208:211], v164 offset:18432
	ds_read_b128 v[212:215], v164 offset:19456
	ds_read_b128 v[216:219], v164 offset:20480
	ds_read_b128 v[220:223], v164 offset:21504
	ds_read_b128 v[224:227], v164 offset:22528
	ds_read_b128 v[228:231], v164 offset:23552
	global_load_lds_dwordx4 v[232:233], off
	s_add_i32 m0, s63, 0x2000
	s_add_u32 s82, s14, 0x40000
	v_lshl_add_u64 v[234:235], s[14:15], 0, v[128:129]
	s_addc_u32 s83, s15, 0
	s_add_i32 s63, s71, s6
	global_load_lds_dwordx4 v[234:235], off
	v_lshl_add_u64 v[236:237], s[82:83], 0, v[132:133]
	s_mov_b32 m0, s63
	v_lshl_add_u64 v[238:239], s[16:17], 0, v[130:131]
	global_load_lds_dwordx4 v[236:237], off
	v_lshl_add_u64 v[236:237], s[82:83], 0, v[128:129]
	s_add_i32 m0, s63, 0x2000
	s_nop 0
	global_load_lds_dwordx4 v[236:237], off
	v_lshl_add_u64 v[236:237], s[16:17], 0, v[134:135]
	s_mov_b32 m0, s8
	s_nop 0
	global_load_lds_dwordx4 v[236:237], off
	s_mov_b32 m0, s9
	s_nop 0
	global_load_lds_dwordx4 v[238:239], off
	s_waitcnt vmcnt(8)
	s_waitcnt lgkmcnt(0)
	s_barrier
; #define PG8_STAGE(bufoff, gbase, voff) do { _Pragma("unroll") for (int _i = 0; _i < 2; ++_i) \
;         __builtin_amdgcn_global_load_lds((const unsigned*)((const char*)(gbase) + (voff)[_i]), (LAS unsigned*)(lds + (bufoff) + ldsw + _i * 8192), 16, 0, 0); } while (0)
; #define PG8_LDA(dst, b, h) do { _Pragma("unroll") for (int m = 0; m < 4; ++m) _Pragma("unroll") for (int k = 0; k < 2; ++k) dst[m][k] = *(const LAS bf16x8*)(lds + PG8_SA(b, h) + aoff + m * 2048 + k * 1024); } while (0)
; #define PG8_LDB(dst, b, h) do { _Pragma("unroll") for (int n = 0; n < 2; ++n) _Pragma("unroll") for (int k = 0; k < 2; ++k) dst[n][k] = *(const LAS bf16x8*)(lds + PG8_SB(b, h) + boff + n * 2048 + k * 1024); } while (0)
; #define PG8_MMA(ai, bj, At, Bt) do { __builtin_amdgcn_s_setprio(1); _Pragma("unroll") for (int m = 0; m < 4; ++m) _Pragma("unroll") for (int n = 0; n < 2; ++n) _Pragma("unroll") for (int k = 0; k < 2; ++k) \
;         acc[ai][bj][m][n] = __builtin_amdgcn_mfma_f32_16x16x32_bf16(Bt[n][k], At[m][k], acc[ai][bj][m][n], 0, 0, 0); __builtin_amdgcn_s_setprio(0); } while (0)
; #define PG8_WAIT_V(n) asm volatile("s_waitcnt vmcnt(" #n ")" ::: "memory")
; #define PG8_WAIT_L(n) asm volatile("s_waitcnt lgkmcnt(" #n ")" ::: "memory")
; #define PG8_BAR __builtin_amdgcn_s_barrier()
; #define PG8_SCHED __builtin_amdgcn_sched_barrier(0)
; template <class Epi, class Sched>
; __device__ __forceinline__ void gemm_phase(LAS unsigned char* lds, const Gemm g, const Sched& S, const Epi& E) {
;     ...
;             PG8_WAIT_V(8); PG8_WAIT_L(0); PG8_BAR; PG8_MMA(1, 0, At, B0); PG8_MMA(1, 1, At, B1); PG8_BAR; PG8_SCHED;
;             PG8_LDB(B0, 1, 0); PG8_LDB(B1, 1, 1); PG8_SCHED; PG8_LDA(At, 1, 0); PG8_STAGE(PG8_SA(0, 1), a2 + hstepA, voffA);
;             PG8_WAIT_V(8); PG8_WAIT_L(0); PG8_BAR; PG8_MMA(0, 0, At, B0); PG8_MMA(0, 1, At, B1); PG8_BAR; PG8_SCHED;
	s_waitcnt lgkmcnt(0)
	v_mfma_f32_16x16x32_bf16 v[60:63], v[140:143], v[200:203], v[60:63]
	v_mfma_f32_16x16x32_bf16 v[56:59], v[166:169], v[200:203], v[56:59]
	v_mfma_f32_16x16x32_bf16 v[44:47], v[140:143], v[208:211], v[44:47]
	v_mfma_f32_16x16x32_bf16 v[40:43], v[166:169], v[208:211], v[40:43]
	v_mfma_f32_16x16x32_bf16 v[28:31], v[140:143], v[216:219], v[28:31]
	v_mfma_f32_16x16x32_bf16 v[24:27], v[166:169], v[216:219], v[24:27]
	v_mfma_f32_16x16x32_bf16 v[12:15], v[140:143], v[224:227], v[12:15]
	v_mfma_f32_16x16x32_bf16 v[8:11], v[166:169], v[224:227], v[8:11]
	v_mfma_f32_16x16x32_bf16 v[60:63], v[156:159], v[204:207], v[60:63]
	v_mfma_f32_16x16x32_bf16 v[56:59], v[170:173], v[204:207], v[56:59]
	v_mfma_f32_16x16x32_bf16 v[44:47], v[156:159], v[212:215], v[44:47]
	v_mfma_f32_16x16x32_bf16 v[40:43], v[170:173], v[212:215], v[40:43]
	v_mfma_f32_16x16x32_bf16 v[28:31], v[156:159], v[220:223], v[28:31]
	v_mfma_f32_16x16x32_bf16 v[24:27], v[170:173], v[220:223], v[24:27]
	v_mfma_f32_16x16x32_bf16 v[12:15], v[156:159], v[228:231], v[12:15]
	v_mfma_f32_16x16x32_bf16 v[8:11], v[170:173], v[228:231], v[8:11]
	v_mfma_f32_16x16x32_bf16 v[52:55], v[174:177], v[200:203], v[52:55]
	v_mfma_f32_16x16x32_bf16 v[48:51], v[192:195], v[200:203], v[48:51]
	v_mfma_f32_16x16x32_bf16 v[36:39], v[174:177], v[208:211], v[36:39]
	v_mfma_f32_16x16x32_bf16 v[32:35], v[192:195], v[208:211], v[32:35]
	v_mfma_f32_16x16x32_bf16 v[20:23], v[174:177], v[216:219], v[20:23]
	v_mfma_f32_16x16x32_bf16 v[16:19], v[192:195], v[216:219], v[16:19]
	v_mfma_f32_16x16x32_bf16 v[4:7], v[174:177], v[224:227], v[4:7]
	v_mfma_f32_16x16x32_bf16 v[0:3], v[192:195], v[224:227], v[0:3]
	v_mfma_f32_16x16x32_bf16 v[52:55], v[180:183], v[204:207], v[52:55]
	v_mfma_f32_16x16x32_bf16 v[48:51], v[196:199], v[204:207], v[48:51]
	v_mfma_f32_16x16x32_bf16 v[36:39], v[180:183], v[212:215], v[36:39]
	v_mfma_f32_16x16x32_bf16 v[32:35], v[196:199], v[212:215], v[32:35]
	v_mfma_f32_16x16x32_bf16 v[20:23], v[180:183], v[220:223], v[20:23]
	v_mfma_f32_16x16x32_bf16 v[16:19], v[196:199], v[220:223], v[16:19]
	v_mfma_f32_16x16x32_bf16 v[4:7], v[180:183], v[228:231], v[4:7]
	v_mfma_f32_16x16x32_bf16 v[0:3], v[196:199], v[228:231], v[0:3]
	s_barrier
	s_add_i32 s63, 0, 0x18000
	v_add_u32_e32 v144, s63, v162
	s_add_i32 s71, 0, 0x1c000
	ds_read_b128 v[140:143], v144
	ds_read_b128 v[156:159], v144 offset:1024
	ds_read_b128 v[166:169], v144 offset:2048
	ds_read_b128 v[170:173], v144 offset:3072
	v_add_u32_e32 v144, s71, v162
	ds_read_b128 v[174:177], v144
	ds_read_b128 v[180:183], v144 offset:1024
	ds_read_b128 v[192:195], v144 offset:2048
	ds_read_b128 v[196:199], v144 offset:3072
	s_add_u32 s16, s16, 0x40000
	s_addc_u32 s17, s17, 0
	s_mov_b32 m0, s10
	v_lshl_add_u64 v[240:241], s[16:17], 0, v[134:135]
	ds_read_b128 v[200:203], v164 offset:32768
	ds_read_b128 v[204:207], v164 offset:33792
	ds_read_b128 v[208:211], v164 offset:34816
	ds_read_b128 v[212:215], v164 offset:35840
	ds_read_b128 v[216:219], v164 offset:36864
	ds_read_b128 v[220:223], v164 offset:37888
	ds_read_b128 v[224:227], v164 offset:38912
	ds_read_b128 v[228:231], v164 offset:39936
	global_load_lds_dwordx4 v[240:241], off
	v_lshl_add_u64 v[240:241], s[16:17], 0, v[130:131]
	s_mov_b32 m0, s11
	s_nop 0
	global_load_lds_dwordx4 v[240:241], off
	s_waitcnt vmcnt(8)
	s_waitcnt lgkmcnt(0)
	s_barrier
	s_waitcnt lgkmcnt(0)
	v_mfma_f32_16x16x32_bf16 v[124:127], v[140:143], v[200:203], v[124:127]
	v_mfma_f32_16x16x32_bf16 v[120:123], v[166:169], v[200:203], v[120:123]
	v_mfma_f32_16x16x32_bf16 v[108:111], v[140:143], v[208:211], v[108:111]
	v_mfma_f32_16x16x32_bf16 v[104:107], v[166:169], v[208:211], v[104:107]
	v_mfma_f32_16x16x32_bf16 v[92:95], v[140:143], v[216:219], v[92:95]
	v_mfma_f32_16x16x32_bf16 v[88:91], v[166:169], v[216:219], v[88:91]
	v_mfma_f32_16x16x32_bf16 v[76:79], v[140:143], v[224:227], v[76:79]
	v_mfma_f32_16x16x32_bf16 v[72:75], v[166:169], v[224:227], v[72:75]
	v_mfma_f32_16x16x32_bf16 v[124:127], v[156:159], v[204:207], v[124:127]
	v_mfma_f32_16x16x32_bf16 v[120:123], v[170:173], v[204:207], v[120:123]
	v_mfma_f32_16x16x32_bf16 v[108:111], v[156:159], v[212:215], v[108:111]
	v_mfma_f32_16x16x32_bf16 v[104:107], v[170:173], v[212:215], v[104:107]
	v_mfma_f32_16x16x32_bf16 v[92:95], v[156:159], v[220:223], v[92:95]
	v_mfma_f32_16x16x32_bf16 v[88:91], v[170:173], v[220:223], v[88:91]
	v_mfma_f32_16x16x32_bf16 v[76:79], v[156:159], v[228:231], v[76:79]
	v_mfma_f32_16x16x32_bf16 v[72:75], v[170:173], v[228:231], v[72:75]
	v_mfma_f32_16x16x32_bf16 v[116:119], v[174:177], v[200:203], v[116:119]
	v_mfma_f32_16x16x32_bf16 v[112:115], v[192:195], v[200:203], v[112:115]
	v_mfma_f32_16x16x32_bf16 v[100:103], v[174:177], v[208:211], v[100:103]
	v_mfma_f32_16x16x32_bf16 v[96:99], v[192:195], v[208:211], v[96:99]
	v_mfma_f32_16x16x32_bf16 v[84:87], v[174:177], v[216:219], v[84:87]
	v_mfma_f32_16x16x32_bf16 v[80:83], v[192:195], v[216:219], v[80:83]
	v_mfma_f32_16x16x32_bf16 v[68:71], v[174:177], v[224:227], v[68:71]
	v_mfma_f32_16x16x32_bf16 v[64:67], v[192:195], v[224:227], v[64:67]
	v_mfma_f32_16x16x32_bf16 v[116:119], v[180:183], v[204:207], v[116:119]
	v_mfma_f32_16x16x32_bf16 v[112:115], v[196:199], v[204:207], v[112:115]
	v_mfma_f32_16x16x32_bf16 v[100:103], v[180:183], v[212:215], v[100:103]
	v_mfma_f32_16x16x32_bf16 v[96:99], v[196:199], v[212:215], v[96:99]
	v_mfma_f32_16x16x32_bf16 v[84:87], v[180:183], v[220:223], v[84:87]
	v_mfma_f32_16x16x32_bf16 v[80:83], v[196:199], v[220:223], v[80:83]
	v_mfma_f32_16x16x32_bf16 v[68:71], v[180:183], v[228:231], v[68:71]
	v_mfma_f32_16x16x32_bf16 v[64:67], v[196:199], v[228:231], v[64:67]
	s_barrier
; #define PG8_STAGE(bufoff, gbase, voff) do { _Pragma("unroll") for (int _i = 0; _i < 2; ++_i) \
;         __builtin_amdgcn_global_load_lds((const unsigned*)((const char*)(gbase) + (voff)[_i]), (LAS unsigned*)(lds + (bufoff) + ldsw + _i * 8192), 16, 0, 0); } while (0)
; #define PG8_LDA(dst, b, h) do { _Pragma("unroll") for (int m = 0; m < 4; ++m) _Pragma("unroll") for (int k = 0; k < 2; ++k) dst[m][k] = *(const LAS bf16x8*)(lds + PG8_SA(b, h) + aoff + m * 2048 + k * 1024); } while (0)
; #define PG8_MMA(ai, bj, At, Bt) do { __builtin_amdgcn_s_setprio(1); _Pragma("unroll") for (int m = 0; m < 4; ++m) _Pragma("unroll") for (int n = 0; n < 2; ++n) _Pragma("unroll") for (int k = 0; k < 2; ++k) \
;         acc[ai][bj][m][n] = __builtin_amdgcn_mfma_f32_16x16x32_bf16(Bt[n][k], At[m][k], acc[ai][bj][m][n], 0, 0, 0); __builtin_amdgcn_s_setprio(0); } while (0)
; #define PG8_WAIT_V(n) asm volatile("s_waitcnt vmcnt(" #n ")" ::: "memory")
; #define PG8_WAIT_L(n) asm volatile("s_waitcnt lgkmcnt(" #n ")" ::: "memory")
; #define PG8_BAR __builtin_amdgcn_s_barrier()
; #define PG8_SCHED __builtin_amdgcn_sched_barrier(0)
; template <class Epi, class Sched>
; __device__ __forceinline__ void gemm_phase(LAS unsigned char* lds, const Gemm g, const Sched& S, const Epi& E) {
;     ...
;             PG8_LDA(At, 1, 1); PG8_STAGE(PG8_SB(1, 0), b3, voffB); PG8_STAGE(PG8_SB(1, 1), b3 + hstepB, voffB); PG8_STAGE(PG8_SA(1, 0), a3, voffA);
;             PG8_WAIT_V(8); PG8_WAIT_L(0); PG8_BAR; PG8_MMA(1, 0, At, B0); PG8_MMA(1, 1, At, B1); PG8_BAR; PG8_SCHED;
;         }
;         if (wr == 0) PG8_BAR;
	s_add_i32 s16, s63, s6
	v_lshl_add_u64 v[232:233], v[232:233], 0, s[0:1]
	s_mov_b32 m0, s16
	ds_read_b128 v[200:203], v164 offset:49152
	ds_read_b128 v[204:207], v164 offset:50176
	ds_read_b128 v[208:211], v164 offset:51200
	ds_read_b128 v[212:215], v164 offset:52224
	ds_read_b128 v[216:219], v164 offset:53248
	ds_read_b128 v[220:223], v164 offset:54272
	ds_read_b128 v[224:227], v164 offset:55296
	ds_read_b128 v[228:231], v164 offset:56320
	global_load_lds_dwordx4 v[232:233], off
	s_add_i32 m0, s16, 0x2000
	s_add_u32 s14, s14, 0x40080
	v_lshl_add_u64 v[232:233], v[234:235], 0, s[0:1]
	s_addc_u32 s15, s15, 0
	s_add_i32 s16, s71, s6
	global_load_lds_dwordx4 v[232:233], off
	v_lshl_add_u64 v[232:233], s[14:15], 0, v[132:133]
	s_mov_b32 m0, s16
	s_nop 0
	global_load_lds_dwordx4 v[232:233], off
	v_lshl_add_u64 v[232:233], s[14:15], 0, v[128:129]
	s_add_i32 m0, s16, 0x2000
	s_nop 0
	global_load_lds_dwordx4 v[232:233], off
	v_lshl_add_u64 v[232:233], v[236:237], 0, s[0:1]
	s_mov_b32 m0, s37
	s_nop 0
	global_load_lds_dwordx4 v[232:233], off
	v_lshl_add_u64 v[232:233], v[238:239], 0, s[0:1]
	s_mov_b32 m0, s38
	s_nop 0
	global_load_lds_dwordx4 v[232:233], off
	s_waitcnt vmcnt(8)
	s_waitcnt lgkmcnt(0)
	s_barrier
	s_waitcnt lgkmcnt(0)
	v_mfma_f32_16x16x32_bf16 v[60:63], v[140:143], v[200:203], v[60:63]
	v_mfma_f32_16x16x32_bf16 v[56:59], v[166:169], v[200:203], v[56:59]
	v_mfma_f32_16x16x32_bf16 v[44:47], v[140:143], v[208:211], v[44:47]
	v_mfma_f32_16x16x32_bf16 v[40:43], v[166:169], v[208:211], v[40:43]
	v_mfma_f32_16x16x32_bf16 v[28:31], v[140:143], v[216:219], v[28:31]
	v_mfma_f32_16x16x32_bf16 v[24:27], v[166:169], v[216:219], v[24:27]
	v_mfma_f32_16x16x32_bf16 v[12:15], v[140:143], v[224:227], v[12:15]
	v_mfma_f32_16x16x32_bf16 v[8:11], v[166:169], v[224:227], v[8:11]
	v_mfma_f32_16x16x32_bf16 v[60:63], v[156:159], v[204:207], v[60:63]
	v_mfma_f32_16x16x32_bf16 v[56:59], v[170:173], v[204:207], v[56:59]
	v_mfma_f32_16x16x32_bf16 v[44:47], v[156:159], v[212:215], v[44:47]
	v_mfma_f32_16x16x32_bf16 v[40:43], v[170:173], v[212:215], v[40:43]
	v_mfma_f32_16x16x32_bf16 v[28:31], v[156:159], v[220:223], v[28:31]
	v_mfma_f32_16x16x32_bf16 v[24:27], v[170:173], v[220:223], v[24:27]
	v_mfma_f32_16x16x32_bf16 v[12:15], v[156:159], v[228:231], v[12:15]
	v_mfma_f32_16x16x32_bf16 v[8:11], v[170:173], v[228:231], v[8:11]
	v_mfma_f32_16x16x32_bf16 v[52:55], v[174:177], v[200:203], v[52:55]
	v_mfma_f32_16x16x32_bf16 v[48:51], v[192:195], v[200:203], v[48:51]
	v_mfma_f32_16x16x32_bf16 v[36:39], v[174:177], v[208:211], v[36:39]
	v_mfma_f32_16x16x32_bf16 v[32:35], v[192:195], v[208:211], v[32:35]
	v_mfma_f32_16x16x32_bf16 v[20:23], v[174:177], v[216:219], v[20:23]
	v_mfma_f32_16x16x32_bf16 v[16:19], v[192:195], v[216:219], v[16:19]
	v_mfma_f32_16x16x32_bf16 v[4:7], v[174:177], v[224:227], v[4:7]
	v_mfma_f32_16x16x32_bf16 v[0:3], v[192:195], v[224:227], v[0:3]
	v_mfma_f32_16x16x32_bf16 v[52:55], v[180:183], v[204:207], v[52:55]
	v_mfma_f32_16x16x32_bf16 v[48:51], v[196:199], v[204:207], v[48:51]
	v_mfma_f32_16x16x32_bf16 v[36:39], v[180:183], v[212:215], v[36:39]
	v_mfma_f32_16x16x32_bf16 v[32:35], v[196:199], v[212:215], v[32:35]
	v_mfma_f32_16x16x32_bf16 v[20:23], v[180:183], v[220:223], v[20:23]
	v_mfma_f32_16x16x32_bf16 v[16:19], v[196:199], v[220:223], v[16:19]
	v_mfma_f32_16x16x32_bf16 v[4:7], v[180:183], v[228:231], v[4:7]
	v_mfma_f32_16x16x32_bf16 v[0:3], v[196:199], v[228:231], v[0:3]
	s_barrier
	s_add_i32 s62, s62, 2
	s_add_u32 s42, s42, 0x100
	s_addc_u32 s43, s43, 0
	s_add_u32 s60, s60, 0x100
	s_addc_u32 s61, s61, 0
	s_cmp_gt_u32 s62, 13
	s_cbranch_scc0 .LBB0_261
	s_and_b64 vcc, exec, s[50:51]
	s_cbranch_vccz .LBB0_264
	s_barrier

; #define PG8_STAGE(bufoff, gbase, voff) do { _Pragma("unroll") for (int _i = 0; _i < 2; ++_i) \
;         __builtin_amdgcn_global_load_lds((const unsigned*)((const char*)(gbase) + (voff)[_i]), (LAS unsigned*)(lds + (bufoff) + ldsw + _i * 8192), 16, 0, 0); } while (0)
; #define PG8_LDA(dst, b, h) do { _Pragma("unroll") for (int m = 0; m < 4; ++m) _Pragma("unroll") for (int k = 0; k < 2; ++k) dst[m][k] = *(const LAS bf16x8*)(lds + PG8_SA(b, h) + aoff + m * 2048 + k * 1024); } while (0)
; #define PG8_LDB(dst, b, h) do { _Pragma("unroll") for (int n = 0; n < 2; ++n) _Pragma("unroll") for (int k = 0; k < 2; ++k) dst[n][k] = *(const LAS bf16x8*)(lds + PG8_SB(b, h) + boff + n * 2048 + k * 1024); } while (0)
; #define PG8_MMA(ai, bj, At, Bt) do { __builtin_amdgcn_s_setprio(1); _Pragma("unroll") for (int m = 0; m < 4; ++m) _Pragma("unroll") for (int n = 0; n < 2; ++n) _Pragma("unroll") for (int k = 0; k < 2; ++k) \
;         acc[ai][bj][m][n] = __builtin_amdgcn_mfma_f32_16x16x32_bf16(Bt[n][k], At[m][k], acc[ai][bj][m][n], 0, 0, 0); __builtin_amdgcn_s_setprio(0); } while (0)
; #define PG8_WAIT_V(n) asm volatile("s_waitcnt vmcnt(" #n ")" ::: "memory")
; #define PG8_WAIT_L(n) asm volatile("s_waitcnt lgkmcnt(" #n ")" ::: "memory")
; #define PG8_BAR __builtin_amdgcn_s_barrier()
; #define PG8_SCHED __builtin_amdgcn_sched_barrier(0)
; template <class Epi, class Sched>
; __device__ __forceinline__ void gemm_phase(LAS unsigned char* lds, const Gemm g, const Sched& S, const Epi& E) {
;     ...
;             PG8_LDB(B0, 0, 0); PG8_LDB(B1, 0, 1); PG8_SCHED; PG8_LDA(At, 0, 0); PG8_STAGE(PG8_SA(1, 1), a1 + hstepA, voffA);
;             PG8_WAIT_V(8); PG8_WAIT_L(0); PG8_BAR; PG8_MMA(0, 0, At, B0); PG8_MMA(0, 1, At, B1); PG8_BAR; PG8_SCHED;
;             PG8_LDA(At, 0, 1); PG8_STAGE(PG8_SB(0, 0), b2, voffB); PG8_STAGE(PG8_SB(0, 1), b2 + hstepB, voffB); PG8_STAGE(PG8_SA(0, 0), a2, voffA);
.LBB0_759:
	s_add_u32 s14, s40, 0xfff00080
	s_addc_u32 s15, s41, -1
	s_add_i32 s63, 0, 0x10000
	s_cmp_eq_u32 s57, 20
	s_cselect_b32 s17, s18, s15
	s_cselect_b32 s16, s19, s14
	v_add_u32_e32 v138, s63, v141
	s_cselect_b32 s15, s59, s47
	s_cselect_b32 s14, s58, s46
	s_add_i32 s69, 0, 0x14000
	ds_read_b128 v[156:159], v138
	ds_read_b128 v[160:163], v138 offset:1024
	ds_read_b128 v[164:167], v138 offset:2048
	ds_read_b128 v[168:171], v138 offset:3072
	v_add_u32_e32 v138, s69, v141
	ds_read_b128 v[172:175], v138
	ds_read_b128 v[180:183], v138 offset:1024
	ds_read_b128 v[196:199], v138 offset:2048
	ds_read_b128 v[200:203], v138 offset:3072
	v_lshl_add_u64 v[138:139], s[40:41], 0, v[134:135]
	s_add_i32 m0, s9, 0xc000
	ds_read_b128 v[204:207], v143
	ds_read_b128 v[208:211], v143 offset:1024
	ds_read_b128 v[212:215], v143 offset:2048
	ds_read_b128 v[216:219], v143 offset:3072
	ds_read_b128 v[220:223], v143 offset:4096
	ds_read_b128 v[224:227], v143 offset:5120
	ds_read_b128 v[228:231], v143 offset:6144
	ds_read_b128 v[232:235], v143 offset:7168
	global_load_lds_dwordx4 v[138:139], off
	v_lshl_add_u64 v[138:139], s[40:41], 0, v[136:137]
	s_add_i32 m0, s9, 0xe000
	s_nop 0
	global_load_lds_dwordx4 v[138:139], off
	s_waitcnt vmcnt(8)
	s_waitcnt lgkmcnt(0)
	s_barrier
	s_waitcnt lgkmcnt(0)
	v_mfma_f32_16x16x32_bf16 v[124:127], v[156:159], v[204:207], v[124:127]
	v_mfma_f32_16x16x32_bf16 v[120:123], v[164:167], v[204:207], v[120:123]
	v_mfma_f32_16x16x32_bf16 v[108:111], v[156:159], v[212:215], v[108:111]
	v_mfma_f32_16x16x32_bf16 v[104:107], v[164:167], v[212:215], v[104:107]
	v_mfma_f32_16x16x32_bf16 v[100:103], v[156:159], v[220:223], v[100:103]
	v_mfma_f32_16x16x32_bf16 v[96:99], v[164:167], v[220:223], v[96:99]
	v_mfma_f32_16x16x32_bf16 v[84:87], v[156:159], v[228:231], v[84:87]
	v_mfma_f32_16x16x32_bf16 v[80:83], v[164:167], v[228:231], v[80:83]
	v_mfma_f32_16x16x32_bf16 v[124:127], v[160:163], v[208:211], v[124:127]
	v_mfma_f32_16x16x32_bf16 v[120:123], v[168:171], v[208:211], v[120:123]
	v_mfma_f32_16x16x32_bf16 v[108:111], v[160:163], v[216:219], v[108:111]
	v_mfma_f32_16x16x32_bf16 v[104:107], v[168:171], v[216:219], v[104:107]
	v_mfma_f32_16x16x32_bf16 v[100:103], v[160:163], v[224:227], v[100:103]
	v_mfma_f32_16x16x32_bf16 v[96:99], v[168:171], v[224:227], v[96:99]
	v_mfma_f32_16x16x32_bf16 v[84:87], v[160:163], v[232:235], v[84:87]
	v_mfma_f32_16x16x32_bf16 v[80:83], v[168:171], v[232:235], v[80:83]
	v_mfma_f32_16x16x32_bf16 v[116:119], v[172:175], v[204:207], v[116:119]
	v_mfma_f32_16x16x32_bf16 v[112:115], v[196:199], v[204:207], v[112:115]
	v_mfma_f32_16x16x32_bf16 v[92:95], v[172:175], v[212:215], v[92:95]
	v_mfma_f32_16x16x32_bf16 v[88:91], v[196:199], v[212:215], v[88:91]
	v_mfma_f32_16x16x32_bf16 v[76:79], v[172:175], v[220:223], v[76:79]
	v_mfma_f32_16x16x32_bf16 v[72:75], v[196:199], v[220:223], v[72:75]
	v_mfma_f32_16x16x32_bf16 v[68:71], v[172:175], v[228:231], v[68:71]
	v_mfma_f32_16x16x32_bf16 v[64:67], v[196:199], v[228:231], v[64:67]
	v_mfma_f32_16x16x32_bf16 v[116:119], v[180:183], v[208:211], v[116:119]
	v_mfma_f32_16x16x32_bf16 v[112:115], v[200:203], v[208:211], v[112:115]
	v_mfma_f32_16x16x32_bf16 v[92:95], v[180:183], v[216:219], v[92:95]
	v_mfma_f32_16x16x32_bf16 v[88:91], v[200:203], v[216:219], v[88:91]
	v_mfma_f32_16x16x32_bf16 v[76:79], v[180:183], v[224:227], v[76:79]
	v_mfma_f32_16x16x32_bf16 v[72:75], v[200:203], v[224:227], v[72:75]
	v_mfma_f32_16x16x32_bf16 v[68:71], v[180:183], v[232:235], v[68:71]
	v_mfma_f32_16x16x32_bf16 v[64:67], v[200:203], v[232:235], v[64:67]
	s_barrier
	s_add_i32 s63, s63, s8
	v_lshl_add_u64 v[138:139], s[14:15], 0, v[144:145]
	s_mov_b32 m0, s63
	ds_read_b128 v[204:207], v143 offset:16384
	ds_read_b128 v[208:211], v143 offset:17408
	ds_read_b128 v[212:215], v143 offset:18432
	ds_read_b128 v[216:219], v143 offset:19456
	ds_read_b128 v[220:223], v143 offset:20480
	ds_read_b128 v[224:227], v143 offset:21504
	ds_read_b128 v[228:231], v143 offset:22528
	ds_read_b128 v[232:235], v143 offset:23552
	global_load_lds_dwordx4 v[138:139], off
	s_add_i32 m0, s63, 0x2000
	s_add_u32 s70, s14, 0x60000
	v_lshl_add_u64 v[176:177], s[14:15], 0, v[128:129]
	s_addc_u32 s71, s15, 0
	s_add_i32 s63, s69, s8
	global_load_lds_dwordx4 v[176:177], off
	v_lshl_add_u64 v[236:237], s[70:71], 0, v[144:145]
	s_mov_b32 m0, s63
	v_lshl_add_u64 v[238:239], s[16:17], 0, v[130:131]
	global_load_lds_dwordx4 v[236:237], off
	v_lshl_add_u64 v[236:237], s[70:71], 0, v[128:129]
	s_add_i32 m0, s63, 0x2000
	s_nop 0
	global_load_lds_dwordx4 v[236:237], off
	v_lshl_add_u64 v[236:237], s[16:17], 0, v[132:133]
	s_mov_b32 m0, s9
	s_nop 0
	global_load_lds_dwordx4 v[236:237], off
	s_mov_b32 m0, s10
	s_nop 0
	global_load_lds_dwordx4 v[238:239], off
	s_waitcnt vmcnt(8)
	s_waitcnt lgkmcnt(0)
	s_barrier
; #define PG8_STAGE(bufoff, gbase, voff) do { _Pragma("unroll") for (int _i = 0; _i < 2; ++_i) \
;         __builtin_amdgcn_global_load_lds((const unsigned*)((const char*)(gbase) + (voff)[_i]), (LAS unsigned*)(lds + (bufoff) + ldsw + _i * 8192), 16, 0, 0); } while (0)
; #define PG8_LDA(dst, b, h) do { _Pragma("unroll") for (int m = 0; m < 4; ++m) _Pragma("unroll") for (int k = 0; k < 2; ++k) dst[m][k] = *(const LAS bf16x8*)(lds + PG8_SA(b, h) + aoff + m * 2048 + k * 1024); } while (0)
; #define PG8_LDB(dst, b, h) do { _Pragma("unroll") for (int n = 0; n < 2; ++n) _Pragma("unroll") for (int k = 0; k < 2; ++k) dst[n][k] = *(const LAS bf16x8*)(lds + PG8_SB(b, h) + boff + n * 2048 + k * 1024); } while (0)
; #define PG8_MMA(ai, bj, At, Bt) do { __builtin_amdgcn_s_setprio(1); _Pragma("unroll") for (int m = 0; m < 4; ++m) _Pragma("unroll") for (int n = 0; n < 2; ++n) _Pragma("unroll") for (int k = 0; k < 2; ++k) \
;         acc[ai][bj][m][n] = __builtin_amdgcn_mfma_f32_16x16x32_bf16(Bt[n][k], At[m][k], acc[ai][bj][m][n], 0, 0, 0); __builtin_amdgcn_s_setprio(0); } while (0)
; #define PG8_WAIT_V(n) asm volatile("s_waitcnt vmcnt(" #n ")" ::: "memory")
; #define PG8_WAIT_L(n) asm volatile("s_waitcnt lgkmcnt(" #n ")" ::: "memory")
; #define PG8_BAR __builtin_amdgcn_s_barrier()
; #define PG8_SCHED __builtin_amdgcn_sched_barrier(0)
; template <class Epi, class Sched>
; __device__ __forceinline__ void gemm_phase(LAS unsigned char* lds, const Gemm g, const Sched& S, const Epi& E) {
;     ...
;             PG8_WAIT_V(8); PG8_WAIT_L(0); PG8_BAR; PG8_MMA(1, 0, At, B0); PG8_MMA(1, 1, At, B1); PG8_BAR; PG8_SCHED;
;             PG8_LDB(B0, 1, 0); PG8_LDB(B1, 1, 1); PG8_SCHED; PG8_LDA(At, 1, 0); PG8_STAGE(PG8_SA(0, 1), a2 + hstepA, voffA);
;             PG8_WAIT_V(8); PG8_WAIT_L(0); PG8_BAR; PG8_MMA(0, 0, At, B0); PG8_MMA(0, 1, At, B1); PG8_BAR; PG8_SCHED;
	s_waitcnt lgkmcnt(0)
	v_mfma_f32_16x16x32_bf16 v[60:63], v[156:159], v[204:207], v[60:63]
	v_mfma_f32_16x16x32_bf16 v[56:59], v[164:167], v[204:207], v[56:59]
	v_mfma_f32_16x16x32_bf16 v[44:47], v[156:159], v[212:215], v[44:47]
	v_mfma_f32_16x16x32_bf16 v[40:43], v[164:167], v[212:215], v[40:43]
	v_mfma_f32_16x16x32_bf16 v[28:31], v[156:159], v[220:223], v[28:31]
	v_mfma_f32_16x16x32_bf16 v[24:27], v[164:167], v[220:223], v[24:27]
	v_mfma_f32_16x16x32_bf16 v[12:15], v[156:159], v[228:231], v[12:15]
	v_mfma_f32_16x16x32_bf16 v[8:11], v[164:167], v[228:231], v[8:11]
	v_mfma_f32_16x16x32_bf16 v[60:63], v[160:163], v[208:211], v[60:63]
	v_mfma_f32_16x16x32_bf16 v[56:59], v[168:171], v[208:211], v[56:59]
	v_mfma_f32_16x16x32_bf16 v[44:47], v[160:163], v[216:219], v[44:47]
	v_mfma_f32_16x16x32_bf16 v[40:43], v[168:171], v[216:219], v[40:43]
	v_mfma_f32_16x16x32_bf16 v[28:31], v[160:163], v[224:227], v[28:31]
	v_mfma_f32_16x16x32_bf16 v[24:27], v[168:171], v[224:227], v[24:27]
	v_mfma_f32_16x16x32_bf16 v[12:15], v[160:163], v[232:235], v[12:15]
	v_mfma_f32_16x16x32_bf16 v[8:11], v[168:171], v[232:235], v[8:11]
	v_mfma_f32_16x16x32_bf16 v[52:55], v[172:175], v[204:207], v[52:55]
	v_mfma_f32_16x16x32_bf16 v[48:51], v[196:199], v[204:207], v[48:51]
	v_mfma_f32_16x16x32_bf16 v[36:39], v[172:175], v[212:215], v[36:39]
	v_mfma_f32_16x16x32_bf16 v[32:35], v[196:199], v[212:215], v[32:35]
	v_mfma_f32_16x16x32_bf16 v[20:23], v[172:175], v[220:223], v[20:23]
	v_mfma_f32_16x16x32_bf16 v[16:19], v[196:199], v[220:223], v[16:19]
	v_mfma_f32_16x16x32_bf16 v[4:7], v[172:175], v[228:231], v[4:7]
	v_mfma_f32_16x16x32_bf16 v[0:3], v[196:199], v[228:231], v[0:3]
	v_mfma_f32_16x16x32_bf16 v[52:55], v[180:183], v[208:211], v[52:55]
	v_mfma_f32_16x16x32_bf16 v[48:51], v[200:203], v[208:211], v[48:51]
	v_mfma_f32_16x16x32_bf16 v[36:39], v[180:183], v[216:219], v[36:39]
	v_mfma_f32_16x16x32_bf16 v[32:35], v[200:203], v[216:219], v[32:35]
	v_mfma_f32_16x16x32_bf16 v[20:23], v[180:183], v[224:227], v[20:23]
	v_mfma_f32_16x16x32_bf16 v[16:19], v[200:203], v[224:227], v[16:19]
	v_mfma_f32_16x16x32_bf16 v[4:7], v[180:183], v[232:235], v[4:7]
	v_mfma_f32_16x16x32_bf16 v[0:3], v[200:203], v[232:235], v[0:3]
	s_barrier
	s_add_i32 s63, 0, 0x18000
	s_add_i32 s69, 0, 0x1c000
	v_add_u32_e32 v168, s63, v141
	v_add_u32_e32 v195, s69, v141
	ds_read_b128 v[156:159], v168
	ds_read_b128 v[160:163], v168 offset:1024
	ds_read_b128 v[164:167], v168 offset:2048
	ds_read_b128 v[168:171], v168 offset:3072
	ds_read_b128 v[172:175], v195
	ds_read_b128 v[180:183], v195 offset:1024
	ds_read_b128 v[196:199], v195 offset:2048
	ds_read_b128 v[200:203], v195 offset:3072
	s_add_u32 s16, s16, 0x100000
	s_addc_u32 s17, s17, 0
	s_mov_b32 m0, s11
	v_lshl_add_u64 v[240:241], s[16:17], 0, v[132:133]
	ds_read_b128 v[204:207], v143 offset:32768
	ds_read_b128 v[208:211], v143 offset:33792
	ds_read_b128 v[212:215], v143 offset:34816
	ds_read_b128 v[216:219], v143 offset:35840
	ds_read_b128 v[220:223], v143 offset:36864
	ds_read_b128 v[224:227], v143 offset:37888
	ds_read_b128 v[228:231], v143 offset:38912
	ds_read_b128 v[232:235], v143 offset:39936
	global_load_lds_dwordx4 v[240:241], off
	v_lshl_add_u64 v[240:241], s[16:17], 0, v[130:131]
	s_mov_b32 m0, s36
	s_nop 0
	global_load_lds_dwordx4 v[240:241], off
	s_waitcnt vmcnt(8)
	s_waitcnt lgkmcnt(0)
	s_barrier
	s_waitcnt lgkmcnt(0)
	v_mfma_f32_16x16x32_bf16 v[124:127], v[156:159], v[204:207], v[124:127]
	v_mfma_f32_16x16x32_bf16 v[120:123], v[164:167], v[204:207], v[120:123]
	v_mfma_f32_16x16x32_bf16 v[108:111], v[156:159], v[212:215], v[108:111]
	v_mfma_f32_16x16x32_bf16 v[104:107], v[164:167], v[212:215], v[104:107]
	v_mfma_f32_16x16x32_bf16 v[100:103], v[156:159], v[220:223], v[100:103]
	v_mfma_f32_16x16x32_bf16 v[96:99], v[164:167], v[220:223], v[96:99]
	v_mfma_f32_16x16x32_bf16 v[84:87], v[156:159], v[228:231], v[84:87]
	v_mfma_f32_16x16x32_bf16 v[80:83], v[164:167], v[228:231], v[80:83]
	v_mfma_f32_16x16x32_bf16 v[124:127], v[160:163], v[208:211], v[124:127]
	v_mfma_f32_16x16x32_bf16 v[120:123], v[168:171], v[208:211], v[120:123]
	v_mfma_f32_16x16x32_bf16 v[108:111], v[160:163], v[216:219], v[108:111]
	v_mfma_f32_16x16x32_bf16 v[104:107], v[168:171], v[216:219], v[104:107]
	v_mfma_f32_16x16x32_bf16 v[100:103], v[160:163], v[224:227], v[100:103]
	v_mfma_f32_16x16x32_bf16 v[96:99], v[168:171], v[224:227], v[96:99]
	v_mfma_f32_16x16x32_bf16 v[84:87], v[160:163], v[232:235], v[84:87]
	v_mfma_f32_16x16x32_bf16 v[80:83], v[168:171], v[232:235], v[80:83]
	v_mfma_f32_16x16x32_bf16 v[116:119], v[172:175], v[204:207], v[116:119]
	v_mfma_f32_16x16x32_bf16 v[112:115], v[196:199], v[204:207], v[112:115]
	v_mfma_f32_16x16x32_bf16 v[92:95], v[172:175], v[212:215], v[92:95]
	v_mfma_f32_16x16x32_bf16 v[88:91], v[196:199], v[212:215], v[88:91]
	v_mfma_f32_16x16x32_bf16 v[76:79], v[172:175], v[220:223], v[76:79]
	v_mfma_f32_16x16x32_bf16 v[72:75], v[196:199], v[220:223], v[72:75]
	v_mfma_f32_16x16x32_bf16 v[68:71], v[172:175], v[228:231], v[68:71]
	v_mfma_f32_16x16x32_bf16 v[64:67], v[196:199], v[228:231], v[64:67]
	v_mfma_f32_16x16x32_bf16 v[116:119], v[180:183], v[208:211], v[116:119]
	v_mfma_f32_16x16x32_bf16 v[112:115], v[200:203], v[208:211], v[112:115]
	v_mfma_f32_16x16x32_bf16 v[92:95], v[180:183], v[216:219], v[92:95]
	v_mfma_f32_16x16x32_bf16 v[88:91], v[200:203], v[216:219], v[88:91]
	v_mfma_f32_16x16x32_bf16 v[76:79], v[180:183], v[224:227], v[76:79]
	v_mfma_f32_16x16x32_bf16 v[72:75], v[200:203], v[224:227], v[72:75]
	v_mfma_f32_16x16x32_bf16 v[68:71], v[180:183], v[232:235], v[68:71]
	v_mfma_f32_16x16x32_bf16 v[64:67], v[200:203], v[232:235], v[64:67]
	s_barrier
; #define PG8_STAGE(bufoff, gbase, voff) do { _Pragma("unroll") for (int _i = 0; _i < 2; ++_i) \
;         __builtin_amdgcn_global_load_lds((const unsigned*)((const char*)(gbase) + (voff)[_i]), (LAS unsigned*)(lds + (bufoff) + ldsw + _i * 8192), 16, 0, 0); } while (0)
; #define PG8_LDA(dst, b, h) do { _Pragma("unroll") for (int m = 0; m < 4; ++m) _Pragma("unroll") for (int k = 0; k < 2; ++k) dst[m][k] = *(const LAS bf16x8*)(lds + PG8_SA(b, h) + aoff + m * 2048 + k * 1024); } while (0)
; #define PG8_MMA(ai, bj, At, Bt) do { __builtin_amdgcn_s_setprio(1); _Pragma("unroll") for (int m = 0; m < 4; ++m) _Pragma("unroll") for (int n = 0; n < 2; ++n) _Pragma("unroll") for (int k = 0; k < 2; ++k) \
;         acc[ai][bj][m][n] = __builtin_amdgcn_mfma_f32_16x16x32_bf16(Bt[n][k], At[m][k], acc[ai][bj][m][n], 0, 0, 0); __builtin_amdgcn_s_setprio(0); } while (0)
; #define PG8_WAIT_V(n) asm volatile("s_waitcnt vmcnt(" #n ")" ::: "memory")
; #define PG8_WAIT_L(n) asm volatile("s_waitcnt lgkmcnt(" #n ")" ::: "memory")
; #define PG8_BAR __builtin_amdgcn_s_barrier()
; #define PG8_SCHED __builtin_amdgcn_sched_barrier(0)
; template <class Epi, class Sched>
; __device__ __forceinline__ void gemm_phase(LAS unsigned char* lds, const Gemm g, const Sched& S, const Epi& E) {
;     ...
;             PG8_LDA(At, 1, 1); PG8_STAGE(PG8_SB(1, 0), b3, voffB); PG8_STAGE(PG8_SB(1, 1), b3 + hstepB, voffB); PG8_STAGE(PG8_SA(1, 0), a3, voffA);
;             PG8_WAIT_V(8); PG8_WAIT_L(0); PG8_BAR; PG8_MMA(1, 0, At, B0); PG8_MMA(1, 1, At, B1); PG8_BAR; PG8_SCHED;
;         }
;         if (wr == 0) PG8_BAR;
	s_add_i32 s16, s63, s8
	v_lshl_add_u64 v[138:139], v[138:139], 0, s[0:1]
	s_mov_b32 m0, s16
	ds_read_b128 v[204:207], v143 offset:49152
	ds_read_b128 v[208:211], v143 offset:50176
	ds_read_b128 v[212:215], v143 offset:51200
	ds_read_b128 v[216:219], v143 offset:52224
	ds_read_b128 v[220:223], v143 offset:53248
	ds_read_b128 v[224:227], v143 offset:54272
	ds_read_b128 v[228:231], v143 offset:55296
	ds_read_b128 v[232:235], v143 offset:56320
	global_load_lds_dwordx4 v[138:139], off
	s_add_i32 m0, s16, 0x2000
	s_add_u32 s14, s14, 0x60080
	v_lshl_add_u64 v[138:139], v[176:177], 0, s[0:1]
	s_addc_u32 s15, s15, 0
	s_add_i32 s16, s69, s8
	global_load_lds_dwordx4 v[138:139], off
	v_lshl_add_u64 v[138:139], s[14:15], 0, v[144:145]
	s_mov_b32 m0, s16
	s_nop 0
	global_load_lds_dwordx4 v[138:139], off
	v_lshl_add_u64 v[138:139], s[14:15], 0, v[128:129]
	s_add_i32 m0, s16, 0x2000
	s_nop 0
	global_load_lds_dwordx4 v[138:139], off
	v_lshl_add_u64 v[138:139], v[236:237], 0, s[0:1]
	s_mov_b32 m0, s37
	s_nop 0
	global_load_lds_dwordx4 v[138:139], off
	v_lshl_add_u64 v[138:139], v[238:239], 0, s[0:1]
	s_mov_b32 m0, s62
	s_nop 0
	global_load_lds_dwordx4 v[138:139], off
	s_waitcnt vmcnt(8)
	s_waitcnt lgkmcnt(0)
	s_barrier
	s_waitcnt lgkmcnt(0)
	v_mfma_f32_16x16x32_bf16 v[60:63], v[156:159], v[204:207], v[60:63]
	v_mfma_f32_16x16x32_bf16 v[56:59], v[164:167], v[204:207], v[56:59]
	v_mfma_f32_16x16x32_bf16 v[44:47], v[156:159], v[212:215], v[44:47]
	v_mfma_f32_16x16x32_bf16 v[40:43], v[164:167], v[212:215], v[40:43]
	v_mfma_f32_16x16x32_bf16 v[28:31], v[156:159], v[220:223], v[28:31]
	v_mfma_f32_16x16x32_bf16 v[24:27], v[164:167], v[220:223], v[24:27]
	v_mfma_f32_16x16x32_bf16 v[12:15], v[156:159], v[228:231], v[12:15]
	v_mfma_f32_16x16x32_bf16 v[8:11], v[164:167], v[228:231], v[8:11]
	v_mfma_f32_16x16x32_bf16 v[60:63], v[160:163], v[208:211], v[60:63]
	v_mfma_f32_16x16x32_bf16 v[56:59], v[168:171], v[208:211], v[56:59]
	v_mfma_f32_16x16x32_bf16 v[44:47], v[160:163], v[216:219], v[44:47]
	v_mfma_f32_16x16x32_bf16 v[40:43], v[168:171], v[216:219], v[40:43]
	v_mfma_f32_16x16x32_bf16 v[28:31], v[160:163], v[224:227], v[28:31]
	v_mfma_f32_16x16x32_bf16 v[24:27], v[168:171], v[224:227], v[24:27]
	v_mfma_f32_16x16x32_bf16 v[12:15], v[160:163], v[232:235], v[12:15]
	v_mfma_f32_16x16x32_bf16 v[8:11], v[168:171], v[232:235], v[8:11]
	v_mfma_f32_16x16x32_bf16 v[52:55], v[172:175], v[204:207], v[52:55]
	v_mfma_f32_16x16x32_bf16 v[48:51], v[196:199], v[204:207], v[48:51]
	v_mfma_f32_16x16x32_bf16 v[36:39], v[172:175], v[212:215], v[36:39]
	v_mfma_f32_16x16x32_bf16 v[32:35], v[196:199], v[212:215], v[32:35]
	v_mfma_f32_16x16x32_bf16 v[20:23], v[172:175], v[220:223], v[20:23]
	v_mfma_f32_16x16x32_bf16 v[16:19], v[196:199], v[220:223], v[16:19]
	v_mfma_f32_16x16x32_bf16 v[4:7], v[172:175], v[228:231], v[4:7]
	v_mfma_f32_16x16x32_bf16 v[0:3], v[196:199], v[228:231], v[0:3]
	v_mfma_f32_16x16x32_bf16 v[52:55], v[180:183], v[208:211], v[52:55]
	v_mfma_f32_16x16x32_bf16 v[48:51], v[200:203], v[208:211], v[48:51]
	v_mfma_f32_16x16x32_bf16 v[36:39], v[180:183], v[216:219], v[36:39]
	v_mfma_f32_16x16x32_bf16 v[32:35], v[200:203], v[216:219], v[32:35]
	v_mfma_f32_16x16x32_bf16 v[20:23], v[180:183], v[224:227], v[20:23]
	v_mfma_f32_16x16x32_bf16 v[16:19], v[200:203], v[224:227], v[16:19]
	v_mfma_f32_16x16x32_bf16 v[4:7], v[180:183], v[232:235], v[4:7]
	v_mfma_f32_16x16x32_bf16 v[0:3], v[200:203], v[232:235], v[0:3]
	s_barrier
	s_add_i32 s57, s57, 2
	s_add_u32 s40, s40, 0x100
	s_addc_u32 s41, s41, 0
	s_add_u32 s46, s46, 0x100
	s_addc_u32 s47, s47, 0
	s_cmp_gt_u32 s57, 21
	s_cbranch_scc0 .LBB0_759
	s_and_b64 vcc, exec, s[54:55]
	s_cbranch_vccz .LBB0_762
	s_barrier

; #define PG8_STAGE(bufoff, gbase, voff) do { _Pragma("unroll") for (int _i = 0; _i < 2; ++_i) \
;         __builtin_amdgcn_global_load_lds((const unsigned*)((const char*)(gbase) + (voff)[_i]), (LAS unsigned*)(lds + (bufoff) + ldsw + _i * 8192), 16, 0, 0); } while (0)
; #define PG8_LDA(dst, b, h) do { _Pragma("unroll") for (int m = 0; m < 4; ++m) _Pragma("unroll") for (int k = 0; k < 2; ++k) dst[m][k] = *(const LAS bf16x8*)(lds + PG8_SA(b, h) + aoff + m * 2048 + k * 1024); } while (0)
; #define PG8_LDB(dst, b, h) do { _Pragma("unroll") for (int n = 0; n < 2; ++n) _Pragma("unroll") for (int k = 0; k < 2; ++k) dst[n][k] = *(const LAS bf16x8*)(lds + PG8_SB(b, h) + boff + n * 2048 + k * 1024); } while (0)
; #define PG8_MMA(ai, bj, At, Bt) do { __builtin_amdgcn_s_setprio(1); _Pragma("unroll") for (int m = 0; m < 4; ++m) _Pragma("unroll") for (int n = 0; n < 2; ++n) _Pragma("unroll") for (int k = 0; k < 2; ++k) \
;         acc[ai][bj][m][n] = __builtin_amdgcn_mfma_f32_16x16x32_bf16(Bt[n][k], At[m][k], acc[ai][bj][m][n], 0, 0, 0); __builtin_amdgcn_s_setprio(0); } while (0)
; #define PG8_WAIT_V(n) asm volatile("s_waitcnt vmcnt(" #n ")" ::: "memory")
; #define PG8_WAIT_L(n) asm volatile("s_waitcnt lgkmcnt(" #n ")" ::: "memory")
; #define PG8_BAR __builtin_amdgcn_s_barrier()
; #define PG8_SCHED __builtin_amdgcn_sched_barrier(0)
; template <class Epi, class Sched>
; __device__ __forceinline__ void gemm_phase(LAS unsigned char* lds, const Gemm g, const Sched& S, const Epi& E) {
;     ...
;             PG8_LDB(B0, 0, 0); PG8_LDB(B1, 0, 1); PG8_SCHED; PG8_LDA(At, 0, 0); PG8_STAGE(PG8_SA(1, 1), a1 + hstepA, voffA);
;             PG8_WAIT_V(8); PG8_WAIT_L(0); PG8_BAR; PG8_MMA(0, 0, At, B0); PG8_MMA(0, 1, At, B1); PG8_BAR; PG8_SCHED;
;             PG8_LDA(At, 0, 1); PG8_STAGE(PG8_SB(0, 0), b2, voffB); PG8_STAGE(PG8_SB(0, 1), b2 + hstepB, voffB); PG8_STAGE(PG8_SA(0, 0), a2, voffA);
.LBB0_783:
	s_add_u32 s14, s40, 0xfff00080
	s_addc_u32 s15, s41, -1
	s_add_i32 s46, 0, 0x10000
	s_cmp_eq_u32 s39, 20
	s_cselect_b32 s17, s5, s15
	s_cselect_b32 s16, s18, s14
	s_cselect_b32 s15, s61, s38
	s_cselect_b32 s14, s60, s19
	s_add_i32 s57, 0, 0x14000
	v_add_u32_e32 v52, s46, v173
	v_add_u32_e32 v170, s57, v173
	ds_read_b128 v[24:27], v52
	ds_read_b128 v[28:31], v52 offset:1024
	ds_read_b128 v[48:51], v52 offset:2048
	ds_read_b128 v[52:55], v52 offset:3072
	ds_read_b128 v[166:169], v170
	ds_read_b128 v[180:183], v170 offset:1024
	ds_read_b128 v[196:199], v170 offset:2048
	ds_read_b128 v[200:203], v170 offset:3072
	v_lshl_add_u64 v[170:171], s[40:41], 0, v[162:163]
	s_add_i32 m0, s70, 0xc000
	ds_read_b128 v[204:207], v175
	ds_read_b128 v[208:211], v175 offset:1024
	ds_read_b128 v[212:215], v175 offset:2048
	ds_read_b128 v[216:219], v175 offset:3072
	ds_read_b128 v[220:223], v175 offset:4096
	ds_read_b128 v[224:227], v175 offset:5120
	ds_read_b128 v[228:231], v175 offset:6144
	ds_read_b128 v[232:235], v175 offset:7168
	global_load_lds_dwordx4 v[170:171], off
	v_lshl_add_u64 v[170:171], s[40:41], 0, v[164:165]
	s_add_i32 m0, s70, 0xe000
	s_nop 0
	global_load_lds_dwordx4 v[170:171], off
	s_waitcnt vmcnt(8)
	s_waitcnt lgkmcnt(0)
	s_barrier
	s_waitcnt lgkmcnt(0)
	v_mfma_f32_16x16x32_bf16 v[140:143], v[24:27], v[204:207], v[140:143]
	v_mfma_f32_16x16x32_bf16 v[136:139], v[48:51], v[204:207], v[136:139]
	v_mfma_f32_16x16x32_bf16 v[124:127], v[24:27], v[212:215], v[124:127]
	v_mfma_f32_16x16x32_bf16 v[120:123], v[48:51], v[212:215], v[120:123]
	v_mfma_f32_16x16x32_bf16 v[108:111], v[24:27], v[220:223], v[108:111]
	v_mfma_f32_16x16x32_bf16 v[104:107], v[48:51], v[220:223], v[104:107]
	v_mfma_f32_16x16x32_bf16 v[92:95], v[24:27], v[228:231], v[92:95]
	v_mfma_f32_16x16x32_bf16 v[88:91], v[48:51], v[228:231], v[88:91]
	v_mfma_f32_16x16x32_bf16 v[140:143], v[28:31], v[208:211], v[140:143]
	v_mfma_f32_16x16x32_bf16 v[136:139], v[52:55], v[208:211], v[136:139]
	v_mfma_f32_16x16x32_bf16 v[124:127], v[28:31], v[216:219], v[124:127]
	v_mfma_f32_16x16x32_bf16 v[120:123], v[52:55], v[216:219], v[120:123]
	v_mfma_f32_16x16x32_bf16 v[108:111], v[28:31], v[224:227], v[108:111]
	v_mfma_f32_16x16x32_bf16 v[104:107], v[52:55], v[224:227], v[104:107]
	v_mfma_f32_16x16x32_bf16 v[92:95], v[28:31], v[232:235], v[92:95]
	v_mfma_f32_16x16x32_bf16 v[88:91], v[52:55], v[232:235], v[88:91]
	v_mfma_f32_16x16x32_bf16 v[132:135], v[166:169], v[204:207], v[132:135]
	v_mfma_f32_16x16x32_bf16 v[128:131], v[196:199], v[204:207], v[128:131]
	v_mfma_f32_16x16x32_bf16 v[116:119], v[166:169], v[212:215], v[116:119]
	v_mfma_f32_16x16x32_bf16 v[112:115], v[196:199], v[212:215], v[112:115]
	v_mfma_f32_16x16x32_bf16 v[100:103], v[166:169], v[220:223], v[100:103]
	v_mfma_f32_16x16x32_bf16 v[96:99], v[196:199], v[220:223], v[96:99]
	v_mfma_f32_16x16x32_bf16 v[84:87], v[166:169], v[228:231], v[84:87]
	v_mfma_f32_16x16x32_bf16 v[80:83], v[196:199], v[228:231], v[80:83]
	v_mfma_f32_16x16x32_bf16 v[132:135], v[180:183], v[208:211], v[132:135]
	v_mfma_f32_16x16x32_bf16 v[128:131], v[200:203], v[208:211], v[128:131]
	v_mfma_f32_16x16x32_bf16 v[116:119], v[180:183], v[216:219], v[116:119]
	v_mfma_f32_16x16x32_bf16 v[112:115], v[200:203], v[216:219], v[112:115]
	v_mfma_f32_16x16x32_bf16 v[100:103], v[180:183], v[224:227], v[100:103]
	v_mfma_f32_16x16x32_bf16 v[96:99], v[200:203], v[224:227], v[96:99]
	v_mfma_f32_16x16x32_bf16 v[84:87], v[180:183], v[232:235], v[84:87]
	v_mfma_f32_16x16x32_bf16 v[80:83], v[200:203], v[232:235], v[80:83]
	s_barrier
	s_add_i32 s46, s46, s69
	v_lshl_add_u64 v[170:171], s[14:15], 0, v[144:145]
	s_mov_b32 m0, s46
	ds_read_b128 v[204:207], v175 offset:16384
	ds_read_b128 v[208:211], v175 offset:17408
	ds_read_b128 v[212:215], v175 offset:18432
	ds_read_b128 v[216:219], v175 offset:19456
	ds_read_b128 v[220:223], v175 offset:20480
	ds_read_b128 v[224:227], v175 offset:21504
	ds_read_b128 v[228:231], v175 offset:22528
	ds_read_b128 v[232:235], v175 offset:23552
	global_load_lds_dwordx4 v[170:171], off
	s_add_i32 m0, s46, 0x2000
	s_add_u32 s46, s14, 0x60000
	v_lshl_add_u64 v[236:237], s[14:15], 0, v[156:157]
	s_addc_u32 s47, s15, 0
	s_add_i32 s57, s57, s69
	global_load_lds_dwordx4 v[236:237], off
	v_lshl_add_u64 v[238:239], s[46:47], 0, v[144:145]
	s_mov_b32 m0, s57
	v_lshl_add_u64 v[240:241], s[16:17], 0, v[158:159]
	global_load_lds_dwordx4 v[238:239], off
	v_lshl_add_u64 v[238:239], s[46:47], 0, v[156:157]
	s_add_i32 m0, s57, 0x2000
	s_nop 0
	global_load_lds_dwordx4 v[238:239], off
	v_lshl_add_u64 v[238:239], s[16:17], 0, v[160:161]
	s_mov_b32 m0, s70
	s_nop 0
	global_load_lds_dwordx4 v[238:239], off
	s_mov_b32 m0, s71
	s_nop 0
	global_load_lds_dwordx4 v[240:241], off
	s_waitcnt vmcnt(8)
	s_waitcnt lgkmcnt(0)
	s_barrier
; #define PG8_STAGE(bufoff, gbase, voff) do { _Pragma("unroll") for (int _i = 0; _i < 2; ++_i) \
;         __builtin_amdgcn_global_load_lds((const unsigned*)((const char*)(gbase) + (voff)[_i]), (LAS unsigned*)(lds + (bufoff) + ldsw + _i * 8192), 16, 0, 0); } while (0)
; #define PG8_LDA(dst, b, h) do { _Pragma("unroll") for (int m = 0; m < 4; ++m) _Pragma("unroll") for (int k = 0; k < 2; ++k) dst[m][k] = *(const LAS bf16x8*)(lds + PG8_SA(b, h) + aoff + m * 2048 + k * 1024); } while (0)
; #define PG8_LDB(dst, b, h) do { _Pragma("unroll") for (int n = 0; n < 2; ++n) _Pragma("unroll") for (int k = 0; k < 2; ++k) dst[n][k] = *(const LAS bf16x8*)(lds + PG8_SB(b, h) + boff + n * 2048 + k * 1024); } while (0)
; #define PG8_MMA(ai, bj, At, Bt) do { __builtin_amdgcn_s_setprio(1); _Pragma("unroll") for (int m = 0; m < 4; ++m) _Pragma("unroll") for (int n = 0; n < 2; ++n) _Pragma("unroll") for (int k = 0; k < 2; ++k) \
;         acc[ai][bj][m][n] = __builtin_amdgcn_mfma_f32_16x16x32_bf16(Bt[n][k], At[m][k], acc[ai][bj][m][n], 0, 0, 0); __builtin_amdgcn_s_setprio(0); } while (0)
; #define PG8_WAIT_V(n) asm volatile("s_waitcnt vmcnt(" #n ")" ::: "memory")
; #define PG8_WAIT_L(n) asm volatile("s_waitcnt lgkmcnt(" #n ")" ::: "memory")
; #define PG8_BAR __builtin_amdgcn_s_barrier()
; #define PG8_SCHED __builtin_amdgcn_sched_barrier(0)
; template <class Epi, class Sched>
; __device__ __forceinline__ void gemm_phase(LAS unsigned char* lds, const Gemm g, const Sched& S, const Epi& E) {
;     ...
;             PG8_WAIT_V(8); PG8_WAIT_L(0); PG8_BAR; PG8_MMA(1, 0, At, B0); PG8_MMA(1, 1, At, B1); PG8_BAR; PG8_SCHED;
;             PG8_LDB(B0, 1, 0); PG8_LDB(B1, 1, 1); PG8_SCHED; PG8_LDA(At, 1, 0); PG8_STAGE(PG8_SA(0, 1), a2 + hstepA, voffA);
;             PG8_WAIT_V(8); PG8_WAIT_L(0); PG8_BAR; PG8_MMA(0, 0, At, B0); PG8_MMA(0, 1, At, B1); PG8_BAR; PG8_SCHED;
	s_waitcnt lgkmcnt(0)
	v_mfma_f32_16x16x32_bf16 v[76:79], v[24:27], v[204:207], v[76:79]
	v_mfma_f32_16x16x32_bf16 v[72:75], v[48:51], v[204:207], v[72:75]
	v_mfma_f32_16x16x32_bf16 v[60:63], v[24:27], v[212:215], v[60:63]
	v_mfma_f32_16x16x32_bf16 v[56:59], v[48:51], v[212:215], v[56:59]
	v_mfma_f32_16x16x32_bf16 v[36:39], v[24:27], v[220:223], v[36:39]
	v_mfma_f32_16x16x32_bf16 v[32:35], v[48:51], v[220:223], v[32:35]
	v_mfma_f32_16x16x32_bf16 v[12:15], v[24:27], v[228:231], v[12:15]
	v_mfma_f32_16x16x32_bf16 v[8:11], v[48:51], v[228:231], v[8:11]
	v_mfma_f32_16x16x32_bf16 v[76:79], v[28:31], v[208:211], v[76:79]
	v_mfma_f32_16x16x32_bf16 v[72:75], v[52:55], v[208:211], v[72:75]
	v_mfma_f32_16x16x32_bf16 v[60:63], v[28:31], v[216:219], v[60:63]
	v_mfma_f32_16x16x32_bf16 v[56:59], v[52:55], v[216:219], v[56:59]
	v_mfma_f32_16x16x32_bf16 v[36:39], v[28:31], v[224:227], v[36:39]
	v_mfma_f32_16x16x32_bf16 v[32:35], v[52:55], v[224:227], v[32:35]
	v_mfma_f32_16x16x32_bf16 v[12:15], v[28:31], v[232:235], v[12:15]
	v_mfma_f32_16x16x32_bf16 v[8:11], v[52:55], v[232:235], v[8:11]
	v_mfma_f32_16x16x32_bf16 v[44:47], v[166:169], v[212:215], v[44:47]
	v_mfma_f32_16x16x32_bf16 v[40:43], v[196:199], v[212:215], v[40:43]
	v_mfma_f32_16x16x32_bf16 v[20:23], v[166:169], v[220:223], v[20:23]
	v_mfma_f32_16x16x32_bf16 v[16:19], v[196:199], v[220:223], v[16:19]
	v_mfma_f32_16x16x32_bf16 v[4:7], v[166:169], v[228:231], v[4:7]
	v_mfma_f32_16x16x32_bf16 v[0:3], v[196:199], v[228:231], v[0:3]
	v_mfma_f32_16x16x32_bf16 v[24:27], v[166:169], v[204:207], v[68:71]
	v_mfma_f32_16x16x32_bf16 v[28:31], v[196:199], v[204:207], v[64:67]
	v_mfma_f32_16x16x32_bf16 v[44:47], v[180:183], v[216:219], v[44:47]
	v_mfma_f32_16x16x32_bf16 v[40:43], v[200:203], v[216:219], v[40:43]
	v_mfma_f32_16x16x32_bf16 v[20:23], v[180:183], v[224:227], v[20:23]
	v_mfma_f32_16x16x32_bf16 v[16:19], v[200:203], v[224:227], v[16:19]
	v_mfma_f32_16x16x32_bf16 v[4:7], v[180:183], v[232:235], v[4:7]
	v_mfma_f32_16x16x32_bf16 v[0:3], v[200:203], v[232:235], v[0:3]
	v_mfma_f32_16x16x32_bf16 v[24:27], v[180:183], v[208:211], v[24:27]
	v_mfma_f32_16x16x32_bf16 v[28:31], v[200:203], v[208:211], v[28:31]
	s_barrier
	s_add_i32 s46, 0, 0x18000
	s_add_i32 s47, 0, 0x1c000
	v_add_u32_e32 v68, s46, v173
	v_add_u32_e32 v177, s47, v173
	ds_read_b128 v[48:51], v68
	ds_read_b128 v[52:55], v68 offset:1024
	ds_read_b128 v[64:67], v68 offset:2048
	ds_read_b128 v[68:71], v68 offset:3072
	ds_read_b128 v[166:169], v177
	ds_read_b128 v[180:183], v177 offset:1024
	ds_read_b128 v[196:199], v177 offset:2048
	ds_read_b128 v[200:203], v177 offset:3072
	s_add_u32 s16, s16, 0x100000
	s_addc_u32 s17, s17, 0
	s_mov_b32 m0, s8
	v_lshl_add_u64 v[242:243], s[16:17], 0, v[160:161]
	ds_read_b128 v[204:207], v175 offset:32768
	ds_read_b128 v[208:211], v175 offset:33792
	ds_read_b128 v[212:215], v175 offset:34816
	ds_read_b128 v[216:219], v175 offset:35840
	ds_read_b128 v[220:223], v175 offset:36864
	ds_read_b128 v[224:227], v175 offset:37888
	ds_read_b128 v[228:231], v175 offset:38912
	ds_read_b128 v[232:235], v175 offset:39936
	global_load_lds_dwordx4 v[242:243], off
	v_lshl_add_u64 v[242:243], s[16:17], 0, v[158:159]
	s_mov_b32 m0, s9
	s_nop 0
	global_load_lds_dwordx4 v[242:243], off
	s_waitcnt vmcnt(8)
	s_waitcnt lgkmcnt(0)
	s_barrier
	s_waitcnt lgkmcnt(0)
	v_mfma_f32_16x16x32_bf16 v[140:143], v[48:51], v[204:207], v[140:143]
	v_mfma_f32_16x16x32_bf16 v[136:139], v[64:67], v[204:207], v[136:139]
	v_mfma_f32_16x16x32_bf16 v[124:127], v[48:51], v[212:215], v[124:127]
	v_mfma_f32_16x16x32_bf16 v[120:123], v[64:67], v[212:215], v[120:123]
	v_mfma_f32_16x16x32_bf16 v[108:111], v[48:51], v[220:223], v[108:111]
	v_mfma_f32_16x16x32_bf16 v[104:107], v[64:67], v[220:223], v[104:107]
	v_mfma_f32_16x16x32_bf16 v[92:95], v[48:51], v[228:231], v[92:95]
	v_mfma_f32_16x16x32_bf16 v[88:91], v[64:67], v[228:231], v[88:91]
	v_mfma_f32_16x16x32_bf16 v[140:143], v[52:55], v[208:211], v[140:143]
	v_mfma_f32_16x16x32_bf16 v[136:139], v[68:71], v[208:211], v[136:139]
	v_mfma_f32_16x16x32_bf16 v[124:127], v[52:55], v[216:219], v[124:127]
	v_mfma_f32_16x16x32_bf16 v[120:123], v[68:71], v[216:219], v[120:123]
	v_mfma_f32_16x16x32_bf16 v[108:111], v[52:55], v[224:227], v[108:111]
	v_mfma_f32_16x16x32_bf16 v[104:107], v[68:71], v[224:227], v[104:107]
	v_mfma_f32_16x16x32_bf16 v[92:95], v[52:55], v[232:235], v[92:95]
	v_mfma_f32_16x16x32_bf16 v[88:91], v[68:71], v[232:235], v[88:91]
	v_mfma_f32_16x16x32_bf16 v[132:135], v[166:169], v[204:207], v[132:135]
	v_mfma_f32_16x16x32_bf16 v[128:131], v[196:199], v[204:207], v[128:131]
	v_mfma_f32_16x16x32_bf16 v[116:119], v[166:169], v[212:215], v[116:119]
	v_mfma_f32_16x16x32_bf16 v[112:115], v[196:199], v[212:215], v[112:115]
	v_mfma_f32_16x16x32_bf16 v[100:103], v[166:169], v[220:223], v[100:103]
	v_mfma_f32_16x16x32_bf16 v[96:99], v[196:199], v[220:223], v[96:99]
	v_mfma_f32_16x16x32_bf16 v[84:87], v[166:169], v[228:231], v[84:87]
	v_mfma_f32_16x16x32_bf16 v[80:83], v[196:199], v[228:231], v[80:83]
	v_mfma_f32_16x16x32_bf16 v[132:135], v[180:183], v[208:211], v[132:135]
	v_mfma_f32_16x16x32_bf16 v[128:131], v[200:203], v[208:211], v[128:131]
	v_mfma_f32_16x16x32_bf16 v[116:119], v[180:183], v[216:219], v[116:119]
	v_mfma_f32_16x16x32_bf16 v[112:115], v[200:203], v[216:219], v[112:115]
	v_mfma_f32_16x16x32_bf16 v[100:103], v[180:183], v[224:227], v[100:103]
	v_mfma_f32_16x16x32_bf16 v[96:99], v[200:203], v[224:227], v[96:99]
	v_mfma_f32_16x16x32_bf16 v[84:87], v[180:183], v[232:235], v[84:87]
	v_mfma_f32_16x16x32_bf16 v[80:83], v[200:203], v[232:235], v[80:83]
	s_barrier
; #define PG8_STAGE(bufoff, gbase, voff) do { _Pragma("unroll") for (int _i = 0; _i < 2; ++_i) \
;         __builtin_amdgcn_global_load_lds((const unsigned*)((const char*)(gbase) + (voff)[_i]), (LAS unsigned*)(lds + (bufoff) + ldsw + _i * 8192), 16, 0, 0); } while (0)
; #define PG8_LDA(dst, b, h) do { _Pragma("unroll") for (int m = 0; m < 4; ++m) _Pragma("unroll") for (int k = 0; k < 2; ++k) dst[m][k] = *(const LAS bf16x8*)(lds + PG8_SA(b, h) + aoff + m * 2048 + k * 1024); } while (0)
; #define PG8_MMA(ai, bj, At, Bt) do { __builtin_amdgcn_s_setprio(1); _Pragma("unroll") for (int m = 0; m < 4; ++m) _Pragma("unroll") for (int n = 0; n < 2; ++n) _Pragma("unroll") for (int k = 0; k < 2; ++k) \
;         acc[ai][bj][m][n] = __builtin_amdgcn_mfma_f32_16x16x32_bf16(Bt[n][k], At[m][k], acc[ai][bj][m][n], 0, 0, 0); __builtin_amdgcn_s_setprio(0); } while (0)
; #define PG8_WAIT_V(n) asm volatile("s_waitcnt vmcnt(" #n ")" ::: "memory")
; #define PG8_WAIT_L(n) asm volatile("s_waitcnt lgkmcnt(" #n ")" ::: "memory")
; #define PG8_BAR __builtin_amdgcn_s_barrier()
; #define PG8_SCHED __builtin_amdgcn_sched_barrier(0)
; template <class Epi, class Sched>
; __device__ __forceinline__ void gemm_phase(LAS unsigned char* lds, const Gemm g, const Sched& S, const Epi& E) {
;     ...
;             PG8_LDA(At, 1, 1); PG8_STAGE(PG8_SB(1, 0), b3, voffB); PG8_STAGE(PG8_SB(1, 1), b3 + hstepB, voffB); PG8_STAGE(PG8_SA(1, 0), a3, voffA);
;             PG8_WAIT_V(8); PG8_WAIT_L(0); PG8_BAR; PG8_MMA(1, 0, At, B0); PG8_MMA(1, 1, At, B1); PG8_BAR; PG8_SCHED;
;         }
;         if (wr == 0) PG8_BAR;
	s_add_i32 s16, s46, s69
	v_lshl_add_u64 v[170:171], v[170:171], 0, s[0:1]
	s_mov_b32 m0, s16
	ds_read_b128 v[204:207], v175 offset:49152
	ds_read_b128 v[208:211], v175 offset:50176
	ds_read_b128 v[212:215], v175 offset:51200
	ds_read_b128 v[216:219], v175 offset:52224
	ds_read_b128 v[220:223], v175 offset:53248
	ds_read_b128 v[224:227], v175 offset:54272
	ds_read_b128 v[228:231], v175 offset:55296
	ds_read_b128 v[232:235], v175 offset:56320
	global_load_lds_dwordx4 v[170:171], off
	s_add_i32 m0, s16, 0x2000
	s_add_u32 s14, s14, 0x60080
	v_lshl_add_u64 v[170:171], v[236:237], 0, s[0:1]
	s_addc_u32 s15, s15, 0
	s_add_i32 s16, s47, s69
	global_load_lds_dwordx4 v[170:171], off
	v_lshl_add_u64 v[170:171], s[14:15], 0, v[144:145]
	s_mov_b32 m0, s16
	s_nop 0
	global_load_lds_dwordx4 v[170:171], off
	v_lshl_add_u64 v[170:171], s[14:15], 0, v[156:157]
	s_add_i32 m0, s16, 0x2000
	s_nop 0
	global_load_lds_dwordx4 v[170:171], off
	v_lshl_add_u64 v[170:171], v[238:239], 0, s[0:1]
	s_mov_b32 m0, s10
	s_nop 0
	global_load_lds_dwordx4 v[170:171], off
	v_lshl_add_u64 v[170:171], v[240:241], 0, s[0:1]
	s_mov_b32 m0, s11
	s_nop 0
	global_load_lds_dwordx4 v[170:171], off
	s_waitcnt vmcnt(8)
	s_waitcnt lgkmcnt(0)
	s_barrier
	s_waitcnt lgkmcnt(0)
	v_mfma_f32_16x16x32_bf16 v[76:79], v[48:51], v[204:207], v[76:79]
	v_mfma_f32_16x16x32_bf16 v[72:75], v[64:67], v[204:207], v[72:75]
	v_mfma_f32_16x16x32_bf16 v[60:63], v[48:51], v[212:215], v[60:63]
	v_mfma_f32_16x16x32_bf16 v[56:59], v[64:67], v[212:215], v[56:59]
	v_mfma_f32_16x16x32_bf16 v[36:39], v[48:51], v[220:223], v[36:39]
	v_mfma_f32_16x16x32_bf16 v[32:35], v[64:67], v[220:223], v[32:35]
	v_mfma_f32_16x16x32_bf16 v[12:15], v[48:51], v[228:231], v[12:15]
	v_mfma_f32_16x16x32_bf16 v[8:11], v[64:67], v[228:231], v[8:11]
	v_mfma_f32_16x16x32_bf16 v[76:79], v[52:55], v[208:211], v[76:79]
	v_mfma_f32_16x16x32_bf16 v[72:75], v[68:71], v[208:211], v[72:75]
	v_mfma_f32_16x16x32_bf16 v[60:63], v[52:55], v[216:219], v[60:63]
	v_mfma_f32_16x16x32_bf16 v[56:59], v[68:71], v[216:219], v[56:59]
	v_mfma_f32_16x16x32_bf16 v[36:39], v[52:55], v[224:227], v[36:39]
	v_mfma_f32_16x16x32_bf16 v[32:35], v[68:71], v[224:227], v[32:35]
	v_mfma_f32_16x16x32_bf16 v[12:15], v[52:55], v[232:235], v[12:15]
	v_mfma_f32_16x16x32_bf16 v[8:11], v[68:71], v[232:235], v[8:11]
	v_mfma_f32_16x16x32_bf16 v[24:27], v[166:169], v[204:207], v[24:27]
	v_mfma_f32_16x16x32_bf16 v[68:71], v[180:183], v[208:211], v[24:27]
	v_mfma_f32_16x16x32_bf16 v[24:27], v[196:199], v[204:207], v[28:31]
	v_mfma_f32_16x16x32_bf16 v[64:67], v[200:203], v[208:211], v[24:27]
	v_mfma_f32_16x16x32_bf16 v[24:27], v[166:169], v[212:215], v[44:47]
	v_mfma_f32_16x16x32_bf16 v[44:47], v[180:183], v[216:219], v[24:27]
	v_mfma_f32_16x16x32_bf16 v[24:27], v[196:199], v[212:215], v[40:43]
	v_mfma_f32_16x16x32_bf16 v[20:23], v[166:169], v[220:223], v[20:23]
	v_mfma_f32_16x16x32_bf16 v[16:19], v[196:199], v[220:223], v[16:19]
	v_mfma_f32_16x16x32_bf16 v[4:7], v[166:169], v[228:231], v[4:7]
	v_mfma_f32_16x16x32_bf16 v[0:3], v[196:199], v[228:231], v[0:3]
	v_mfma_f32_16x16x32_bf16 v[40:43], v[200:203], v[216:219], v[24:27]
	v_mfma_f32_16x16x32_bf16 v[20:23], v[180:183], v[224:227], v[20:23]
	v_mfma_f32_16x16x32_bf16 v[16:19], v[200:203], v[224:227], v[16:19]
	v_mfma_f32_16x16x32_bf16 v[4:7], v[180:183], v[232:235], v[4:7]
	v_mfma_f32_16x16x32_bf16 v[0:3], v[200:203], v[232:235], v[0:3]
	s_barrier
	s_add_i32 s39, s39, 2
	s_add_u32 s40, s40, 0x100
	s_addc_u32 s41, s41, 0
	s_add_u32 s19, s19, 0x100
	s_addc_u32 s38, s38, 0
	s_cmp_gt_u32 s39, 21
	s_cbranch_scc0 .LBB0_783
	s_and_b64 vcc, exec, s[54:55]
	s_cbranch_vccz .LBB0_786
	s_barrier
